# v68 + dt loads hoisted into the batched sample prologue loads
# speedup vs baseline: 1.0083x; 1.0083x over previous
.LBB0_833:
	s_or_saveexec_b64 s[0:1], s[0:1]
	v_mov_b32_e32 v48, 7
	s_xor_b64 exec, exec, s[0:1]
	v_mov_b32_e32 v48, 8
	v_lshl_add_u32 v68, s63, 8, v147
	s_or_b64 exec, exec, s[0:1]
	v_ashrrev_i32_e32 v69, 31, v68
	v_readlane_b32 s24, v252, 6
	s_ashr_i32 s0, s62, 3
	v_lshlrev_b64 v[66:67], 2, v[68:69]
	v_readlane_b32 s30, v252, 12
	v_readlane_b32 s31, v252, 13
	s_add_i32 s0, s0, s8
	s_and_b32 s21, s62, -8
	v_lshl_add_u64 v[70:71], s[30:31], 0, v[66:67]
	v_mad_i64_i32 v[70:71], s[6:7], s0, v231, v[70:71]
	v_add_co_u32_e32 v72, vcc, 0x4000, v70
	s_mul_i32 s22, s21, 0x3000
	s_nop 0
	v_addc_co_u32_e32 v73, vcc, 0, v71, vcc
	global_load_dword v138, v[70:71], off
	global_load_dword v139, v[72:73], off
	v_add_co_u32_e32 v70, vcc, 0x8000, v70
	s_add_i32 s1, s21, 0x4000
	s_add_i32 s6, s22, 0xc000000
	v_addc_co_u32_e32 v71, vcc, 0, v71, vcc
	s_mul_hi_i32 s7, s1, 0x3000
	s_add_u32 s6, s4, s6
	global_load_dword v140, v[70:71], off
	s_movk_i32 s23, 0x1000
	v_lshl_add_u32 v71, v68, 1, s23
	v_readlane_b32 s25, v252, 7
	v_readlane_b32 s26, v252, 8
	v_readlane_b32 s27, v252, 9
	v_readlane_b32 s28, v252, 10
	v_readlane_b32 s29, v252, 11
	v_add_u32_e32 v242, s1, v213
	v_lshlrev_b32_e32 v242, 7, v242
	v_lshl_or_b32 v244, s63, 2, v214
	v_lshl_add_u32 v242, v244, 2, v242
	v_readlane_b32 s6, v255, 8
	v_readlane_b32 s7, v255, 9
	v_or_b32_e32 v244, s11, v244
	v_lshlrev_b32_e32 v244, 2, v244
	s_nop 3
	global_load_dword v243, v242, s[6:7]
	v_readlane_b32 s6, v252, 43
	v_readlane_b32 s7, v252, 44
	s_nop 4
	global_load_dword v245, v244, s[6:7]
	s_add_i32 s23, s22, 0xc000000
	s_add_u32 s6, s4, s23
	s_addc_u32 s7, s5, 0
	global_load_ushort v141, v71, s[6:7]
	s_add_i32 s23, s22, 0xc003000
	s_add_u32 s6, s4, s23
	s_addc_u32 s7, s5, 0
	global_load_ushort v148, v71, s[6:7]
	s_add_i32 s23, s22, 0xc006000
	s_add_u32 s6, s4, s23
	s_addc_u32 s7, s5, 0
	global_load_ushort v149, v71, s[6:7]
	s_add_i32 s23, s22, 0xc009000
	s_add_u32 s6, s4, s23
	s_addc_u32 s7, s5, 0
	global_load_ushort v69, v71, s[6:7]
	s_add_i32 s23, s22, 0xc00c000
	s_add_u32 s6, s4, s23
	s_addc_u32 s7, s5, 0
	global_load_ushort v68, v71, s[6:7]
	s_add_i32 s23, s22, 0xc00f000
	s_add_u32 s6, s4, s23
	s_addc_u32 s7, s5, 0
	global_load_ushort v150, v71, s[6:7]
	s_add_i32 s23, s22, 0xc012000
	s_add_u32 s6, s4, s23
	s_addc_u32 s7, s5, 0
	global_load_ushort v72, v71, s[6:7]
	s_add_i32 s23, s22, 0xc015000
	s_add_u32 s6, s4, s23
	s_addc_u32 s7, s5, 0
	global_load_ushort v73, v71, s[6:7]
	global_load_dword v151, v66, s[42:43]
	global_load_dword v152, v66, s[82:83]
	global_load_dword v153, v66, s[86:87]
	global_load_dword v70, v66, s[80:81]
	v_readlane_b32 s6, v252, 47
	v_readlane_b32 s7, v252, 48
	s_nop 4
	global_load_dword v66, v66, s[6:7]
	s_waitcnt vmcnt(0)
	v_lshlrev_b32_e32 v141, 16, v141
	v_lshlrev_b32_e32 v148, 16, v148
	v_lshlrev_b32_e32 v149, 16, v149
	v_lshlrev_b32_e32 v69, 16, v69
	v_lshlrev_b32_e32 v68, 16, v68
	v_lshlrev_b32_e32 v150, 16, v150
	v_lshlrev_b32_e32 v72, 16, v72
	v_lshlrev_b32_e32 v73, 16, v73
	v_fma_f32 v67, v138, v151, v66
	v_fmac_f32_e32 v67, v139, v152
	v_fmac_f32_e32 v67, v140, v153
	v_fmac_f32_e32 v67, v70, v141
	v_mul_f32_e32 v71, 0xbfb8aa3b, v67
	v_exp_f32_e32 v71, v71
	s_nop 0
	v_add_f32_e32 v71, 1.0, v71
	v_rcp_f32_e32 v71, v71
	s_nop 0
	v_mul_f32_e32 v67, v67, v71
	ds_write_b32 v219, v67
	v_fma_f32 v67, v139, v151, v66
	v_fmac_f32_e32 v67, v140, v152
	v_fmac_f32_e32 v67, v153, v141
	v_fmac_f32_e32 v67, v70, v148
	v_mul_f32_e32 v71, 0xbfb8aa3b, v67
	v_exp_f32_e32 v71, v71
	s_nop 0
	v_add_f32_e32 v71, 1.0, v71
	v_rcp_f32_e32 v71, v71
	s_nop 0
	v_mul_f32_e32 v67, v67, v71
	v_lshlrev_b32_e64 v71, v48, 1
	v_lshl_add_u32 v71, v71, 2, v219
	ds_write_b32 v71, v67
	v_fma_f32 v67, v140, v151, v66
	v_fmac_f32_e32 v67, v152, v141
	v_fmac_f32_e32 v67, v153, v148
	v_fmac_f32_e32 v67, v70, v149
	v_mul_f32_e32 v71, 0xbfb8aa3b, v67
	v_exp_f32_e32 v71, v71
	s_nop 0
	v_add_f32_e32 v71, 1.0, v71
	v_rcp_f32_e32 v71, v71
	s_nop 0
	v_mul_f32_e32 v67, v67, v71
	v_lshlrev_b32_e64 v71, v48, 2
	v_lshl_add_u32 v71, v71, 2, v219
	ds_write_b32 v71, v67
	v_fma_f32 v67, v151, v141, v66
	v_fmac_f32_e32 v67, v152, v148
	v_fmac_f32_e32 v67, v153, v149
	v_fmac_f32_e32 v67, v70, v69
	v_mul_f32_e32 v71, 0xbfb8aa3b, v67
	v_exp_f32_e32 v71, v71
	s_nop 0
	v_add_f32_e32 v71, 1.0, v71
	v_rcp_f32_e32 v71, v71
	s_nop 0
	v_mul_f32_e32 v67, v67, v71
	v_lshlrev_b32_e64 v71, v48, 3
	v_lshl_add_u32 v71, v71, 2, v219
	ds_write_b32 v71, v67
	v_fma_f32 v67, v151, v148, v66
	v_fmac_f32_e32 v67, v152, v149
	v_fmac_f32_e32 v67, v153, v69
	v_fmac_f32_e32 v67, v70, v68
	v_mul_f32_e32 v71, 0xbfb8aa3b, v67
	v_exp_f32_e32 v71, v71
	s_nop 0
	v_add_f32_e32 v71, 1.0, v71
	v_rcp_f32_e32 v71, v71
	s_nop 0
	v_mul_f32_e32 v67, v67, v71
	v_lshlrev_b32_e64 v71, v48, 4
	v_lshl_add_u32 v71, v71, 2, v219
	ds_write_b32 v71, v67
	v_fma_f32 v67, v151, v149, v66
	v_fmac_f32_e32 v67, v152, v69
	v_fmac_f32_e32 v67, v153, v68
	v_fmac_f32_e32 v67, v70, v150
	v_mul_f32_e32 v71, 0xbfb8aa3b, v67
	v_exp_f32_e32 v71, v71
	s_nop 0
	v_add_f32_e32 v71, 1.0, v71
	v_rcp_f32_e32 v71, v71
	s_nop 0
	v_mul_f32_e32 v67, v67, v71
	v_lshlrev_b32_e64 v71, v48, 5
	v_lshl_add_u32 v71, v71, 2, v219
	ds_write_b32 v71, v67
	v_fma_f32 v67, v151, v69, v66
	v_fmac_f32_e32 v67, v152, v68
	v_fmac_f32_e32 v67, v153, v150
	v_fmac_f32_e32 v67, v70, v72
	v_mul_f32_e32 v69, 0xbfb8aa3b, v67
	v_exp_f32_e32 v69, v69
	v_fmac_f32_e32 v66, v151, v68
	v_fmac_f32_e32 v66, v152, v150
	v_fmac_f32_e32 v66, v153, v72
	v_add_f32_e32 v69, 1.0, v69
	v_rcp_f32_e32 v69, v69
	v_fmac_f32_e32 v66, v70, v73
	v_mul_f32_e32 v67, v67, v69
	v_lshlrev_b32_e64 v69, v48, 6
	v_lshl_add_u32 v69, v69, 2, v219
	ds_write_b32 v69, v67
	v_mul_f32_e32 v67, 0xbfb8aa3b, v66
	v_exp_f32_e32 v67, v67
	v_lshlrev_b32_e64 v48, v48, 7
	v_lshl_add_u32 v48, v48, 2, v219
	v_add_f32_e32 v67, 1.0, v67
	v_rcp_f32_e32 v67, v67
	s_nop 0
	v_mul_f32_e32 v66, v66, v67
	ds_write_b32 v48, v66
	s_mov_b64 s[6:7], exec
	v_readlane_b32 s22, v255, 14
	v_readlane_b32 s23, v255, 15
	s_and_b64 s[22:23], s[6:7], s[22:23]
	s_mov_b64 exec, s[22:23]
	s_cbranch_execz .LBB0_839
	v_add_u32_e32 v66, s1, v213
	v_ashrrev_i32_e32 v67, 31, v66
	v_readlane_b32 s22, v255, 8
	v_lshl_or_b32 v68, s63, 2, v214
	v_lshlrev_b64 v[66:67], 7, v[66:67]
	v_readlane_b32 s23, v255, 9
	v_lshlrev_b32_e32 v48, 2, v68
	v_readlane_b32 s24, v252, 39
	v_lshl_add_u64 v[66:67], s[22:23], 0, v[66:67]
	v_lshl_add_u64 v[66:67], v[66:67], 0, v[48:49]
	v_or_b32_e32 v48, s11, v68
	v_readlane_b32 s28, v252, 43
	v_readlane_b32 s29, v252, 44
	v_mov_b32_e32 v69, v243
	v_readlane_b32 s25, v252, 40
	v_lshl_add_u64 v[66:67], v[48:49], 2, s[28:29]
	v_mov_b32_e32 v66, v245
	v_readlane_b32 s26, v252, 41
	v_readlane_b32 s27, v252, 42
	v_readlane_b32 s30, v252, 45
	v_readlane_b32 s31, v252, 46
	s_nop 0
	v_add_f32_e32 v66, v69, v66
	v_cmp_nlt_f32_e32 vcc, s19, v66
	s_and_saveexec_b64 s[40:41], vcc
	s_cbranch_execz .LBB0_838
	v_mul_f32_e32 v66, 0x3fb8aa3b, v66
	v_exp_f32_e32 v150, v66
	s_mov_b32 s1, 0x3f317218
	v_add_f32_e32 v68, 1.0, v150
	v_frexp_mant_f32_e32 v70, v68
	v_cvt_f64_f32_e32 v[66:67], v68
	v_frexp_exp_i32_f64_e32 v66, v[66:67]
	v_cmp_gt_f32_e32 vcc, s64, v70
	v_add_f32_e32 v69, -1.0, v68
	v_sub_f32_e32 v71, v69, v68
	v_subbrev_co_u32_e32 v138, vcc, 0, v66, vcc
	v_sub_u32_e32 v66, 0, v138
	v_sub_f32_e32 v69, v150, v69
	v_add_f32_e32 v71, 1.0, v71
	v_ldexp_f32 v67, v68, v66
	v_add_f32_e32 v69, v69, v71
	v_add_f32_e32 v68, -1.0, v67
	v_add_f32_e32 v70, 1.0, v67
	v_ldexp_f32 v66, v69, v66
	v_add_f32_e32 v69, 1.0, v68
	v_add_f32_e32 v71, -1.0, v70
	v_sub_f32_e32 v69, v67, v69
	v_sub_f32_e32 v67, v67, v71
	v_add_f32_e32 v69, v66, v69
	v_add_f32_e32 v66, v66, v67
	v_add_f32_e32 v139, v70, v66
	v_rcp_f32_e32 v141, v139
	v_sub_f32_e32 v67, v139, v70
	v_sub_f32_e32 v140, v66, v67
	v_add_f32_e32 v67, v68, v69
	v_mul_f32_e32 v149, v67, v141
	v_sub_f32_e32 v66, v67, v68
	v_mul_f32_e32 v68, v139, v149
	v_fma_f32 v70, v149, v139, -v68
	v_fmac_f32_e32 v70, v149, v140
	v_sub_f32_e32 v148, v69, v66
	v_add_f32_e32 v66, v68, v70
	v_sub_f32_e32 v69, v67, v66
	v_pk_add_f32 v[72:73], v[66:67], v[68:69] neg_lo:[0,1] neg_hi:[0,1]
	v_mov_b32_e32 v71, v66
	v_pk_add_f32 v[66:67], v[72:73], v[70:71] neg_lo:[0,1] neg_hi:[0,1]
	s_nop 0
	v_add_f32_e32 v67, v148, v67
	v_add_f32_e32 v66, v66, v67
	v_add_f32_e32 v67, v69, v66
	v_mul_f32_e32 v148, v141, v67
	v_mul_f32_e32 v68, v139, v148
	v_fma_f32 v70, v148, v139, -v68
	v_fmac_f32_e32 v70, v148, v140
	v_sub_f32_e32 v69, v69, v67
	v_add_f32_e32 v139, v66, v69
	v_add_f32_e32 v66, v68, v70
	v_sub_f32_e32 v69, v67, v66
	v_pk_add_f32 v[72:73], v[66:67], v[68:69] neg_lo:[0,1] neg_hi:[0,1]
	v_mov_b32_e32 v71, v66
	v_pk_add_f32 v[66:67], v[72:73], v[70:71] neg_lo:[0,1] neg_hi:[0,1]
	s_nop 0
	v_add_f32_e32 v67, v139, v67
	v_add_f32_e32 v66, v66, v67
	v_add_f32_e32 v67, v149, v148
	v_add_f32_e32 v66, v69, v66
	v_sub_f32_e32 v68, v67, v149
	v_mul_f32_e32 v66, v141, v66
	v_sub_f32_e32 v68, v148, v68
	v_add_f32_e32 v68, v68, v66
	v_add_f32_e32 v70, v67, v68
	v_mul_f32_e32 v71, v70, v70
	v_fmamk_f32 v66, v71, 0x3e9b6dac, v236
	v_fmaak_f32 v207, v71, v66, 0x3f2aaada
	v_cvt_f32_i32_e32 v66, v138
	v_sub_f32_e32 v67, v70, v67
	v_sub_f32_e32 v67, v68, v67
	v_ldexp_f32 v72, v67, 1
	v_mul_f32_e32 v67, v70, v71
	v_ldexp_f32 v69, v70, 1
	v_pk_mul_f32 v[70:71], v[66:67], v[206:207]
	s_nop 0
	v_fma_f32 v68, v66, s1, -v70
	v_fmac_f32_e32 v68, 0xb102e308, v66
	v_pk_add_f32 v[66:67], v[70:71], v[68:69]
	s_mov_b32 s1, 0x7f800000
	v_sub_f32_e32 v69, v67, v69
	v_sub_f32_e32 v69, v71, v69
	v_add_f32_e32 v73, v72, v69
	v_mov_b32_e32 v72, v70
	v_pk_add_f32 v[70:71], v[66:67], v[70:71] neg_lo:[0,1] neg_hi:[0,1]
	v_pk_add_f32 v[138:139], v[66:67], v[72:73]
	v_mov_b32_e32 v69, v66
	v_mov_b32_e32 v71, v139
	v_pk_add_f32 v[140:141], v[68:69], v[70:71] neg_lo:[0,1] neg_hi:[0,1]
	v_pk_add_f32 v[68:69], v[68:69], v[70:71]
	v_mov_b32_e32 v72, v73
	v_pk_add_f32 v[70:71], v[68:69], v[66:67] op_sel:[1,0] op_sel_hi:[0,1] neg_lo:[0,1] neg_hi:[0,1]
	v_pk_add_f32 v[148:149], v[138:139], v[70:71] op_sel_hi:[1,0] neg_lo:[0,1] neg_hi:[0,1]
	v_mov_b32_e32 v138, v139
	v_mov_b32_e32 v139, v69
	v_pk_mov_b32 v[70:71], v[66:67], v[70:71] op_sel:[1,0]
	v_mov_b32_e32 v73, v66
	v_pk_add_f32 v[70:71], v[138:139], v[70:71] neg_lo:[0,1] neg_hi:[0,1]
	v_mov_b32_e32 v148, v140
	v_pk_add_f32 v[66:67], v[72:73], v[70:71] neg_lo:[0,1] neg_hi:[0,1]
	v_mov_b32_e32 v141, v69
	v_pk_add_f32 v[70:71], v[148:149], v[66:67]
	v_cmp_neq_f32_e32 vcc, s1, v150
	v_pk_add_f32 v[72:73], v[70:71], v[70:71] op_sel:[0,1] op_sel_hi:[1,0]
	s_mov_b32 s1, 0x33800000
	v_pk_add_f32 v[68:69], v[68:69], v[72:73] op_sel:[1,0] op_sel_hi:[0,1]
	v_mov_b32_e32 v71, v68
	v_pk_add_f32 v[138:139], v[70:71], v[140:141] neg_lo:[0,1] neg_hi:[0,1]
	v_mov_b32_e32 v67, v72
	v_sub_f32_e32 v69, v70, v138
	v_pk_add_f32 v[66:67], v[66:67], v[138:139] neg_lo:[0,1] neg_hi:[0,1]
	v_sub_f32_e32 v69, v140, v69
	v_add_f32_e32 v66, v66, v69
	v_add_f32_e32 v66, v66, v67
	v_add_f32_e32 v66, v68, v66
	v_cndmask_b32_e32 v66, v237, v66, vcc
	v_cmp_ngt_f32_e32 vcc, -1.0, v150
	s_nop 1
	v_cndmask_b32_e32 v66, v238, v66, vcc
	v_cmp_neq_f32_e32 vcc, -1.0, v150
	s_nop 1
	v_cndmask_b32_e32 v66, v239, v66, vcc
	v_cmp_lt_f32_e64 vcc, |v150|, s1
	s_nop 1
	v_cndmask_b32_e32 v66, v66, v150, vcc
